# sgu: the six staging loads of each K-step issued together into dedicated registers, one wait per K-step
# speedup vs baseline: 1.0109x; 1.0109x over previous
.LBB0_169:
	v_ashrrev_i32_e32 v0, 3, v143
	v_lshrrev_b32_e32 v1, 29, v0
	v_add_lshl_u32 v1, v0, v1, 3
	v_and_b32_e32 v1, 0xffffffc0, v1
	v_and_b32_e32 v2, 56, v183
	v_and_b32_e32 v0, 7, v0
	v_or3_b32 v160, v1, v2, v0
	s_mov_b32 s0, 0x2aaaaaab
	v_mul_hi_i32 v0, v160, s0
	v_lshrrev_b32_e32 v1, 31, v0
	v_ashrrev_i32_e32 v0, 5, v0
	v_ashrrev_i32_e32 v161, 31, v160
	v_add_u32_e32 v184, v0, v1
	v_lshlrev_b64 v[0:1], 8, v[160:161]
	v_or_b32_e32 v4, v0, v144
	v_mov_b32_e32 v5, v1
	v_lshlrev_b64 v[4:5], 8, v[4:5]
	v_lshl_add_u64 v[162:163], v[146:147], 0, v[4:5]
	v_or_b32_e32 v4, v0, v148
	v_mov_b32_e32 v5, v1
	v_lshlrev_b64 v[4:5], 8, v[4:5]
	v_lshlrev_b32_e32 v2, 14, v184
	v_lshl_add_u64 v[164:165], v[146:147], 0, v[4:5]
	v_or_b32_e32 v4, v0, v150
	v_or_b32_e32 v0, v0, v152
	v_ashrrev_i32_e32 v3, 31, v2
	v_mov_b32_e32 v5, v1
	v_lshlrev_b64 v[0:1], 8, v[0:1]
	v_lshl_add_u64 v[170:171], v[146:147], 0, v[0:1]
	v_lshl_add_u64 v[168:169], v[2:3], 1, v[154:155]
	v_lshlrev_b64 v[4:5], 8, v[4:5]
	v_lshl_add_u64 v[166:167], v[146:147], 0, v[4:5]
	s_movk_i32 s0, 0x4000
	v_add_co_u32_e32 v172, vcc, s0, v168
	s_movk_i32 s0, 0xc0
	s_nop 0
	v_addc_co_u32_e32 v173, vcc, 0, v169, vcc
	global_load_dwordx4 v[218:221], v[162:163], off
	global_load_dwordx4 v[222:225], v[164:165], off
	global_load_dwordx4 v[226:229], v[166:167], off
	global_load_dwordx4 v[238:241], v[170:171], off
	global_load_dwordx4 v[244:247], v[168:169], off
	global_load_dwordx4 v[248:251], v[172:173], off
	v_mul_lo_u32 v130, v184, s0
	v_sub_u32_e32 v130, v160, v130
	v_lshl_or_b32 v130, v130, 8, v145
	v_ashrrev_i32_e32 v130, 7, v130
	v_ashrrev_i32_e32 v131, 31, v130
	v_lshlrev_b64 v[130:131], 7, v[130:131]
	v_add_u32_e32 v143, s23, v143
	s_movk_i32 s0, 0x2ff
	v_cmp_lt_i32_e32 vcc, s0, v143
	v_add_u32_e32 v183, s20, v183
	s_or_b64 s[8:9], vcc, s[8:9]
	s_waitcnt vmcnt(0)
	ds_write_b128 v149, v[218:221]
	ds_write_b128 v151, v[222:225]
	ds_write_b128 v153, v[226:229]
	ds_write_b128 v157, v[238:241]
	ds_write_b128 v159, v[244:247]
	ds_write_b128 v174, v[248:251]
	s_waitcnt lgkmcnt(0)
	s_barrier
	global_load_dwordx4 v[218:221], v[162:163], off offset:64
	global_load_dwordx4 v[222:225], v[164:165], off offset:64
	global_load_dwordx4 v[226:229], v[166:167], off offset:64
	global_load_dwordx4 v[238:241], v[170:171], off offset:64
	global_load_dwordx4 v[244:247], v[168:169], off offset:64
	global_load_dwordx4 v[248:251], v[172:173], off offset:64
	ds_read_b128 v[0:3], v175 offset:2560
	ds_read_b128 v[4:7], v175 offset:5120
	ds_read_b128 v[8:11], v175 offset:7680
	ds_read_b128 v[12:15], v176 offset:23040
	ds_read_b128 v[16:19], v175
	ds_read_b128 v[186:189], v175 offset:32
	ds_read_b128 v[64:67], v176 offset:20480
	ds_read_b128 v[190:193], v176 offset:20512
	s_waitcnt lgkmcnt(1)
	v_mfma_f32_32x32x16_bf16 v[112:127], v[16:19], v[64:67], 0
	ds_read_b128 v[194:197], v175 offset:2592
	ds_read_b128 v[198:201], v175 offset:5152
	ds_read_b128 v[202:205], v175 offset:7712
	ds_read_b128 v[206:209], v176 offset:23072
	v_mfma_f32_32x32x16_bf16 v[48:63], v[16:19], v[12:15], 0
	s_waitcnt lgkmcnt(4)
	v_mfma_f32_32x32x16_bf16 v[112:127], v[186:189], v[190:193], v[112:127]
	s_waitcnt lgkmcnt(0)
	v_mfma_f32_32x32x16_bf16 v[48:63], v[186:189], v[206:209], v[48:63]
	v_mfma_f32_32x32x16_bf16 v[96:111], v[0:3], v[64:67], 0
	v_mfma_f32_32x32x16_bf16 v[32:47], v[0:3], v[12:15], 0
	v_mfma_f32_32x32x16_bf16 v[80:95], v[4:7], v[64:67], 0
	v_mfma_f32_32x32x16_bf16 v[16:31], v[4:7], v[12:15], 0
	v_mfma_f32_32x32x16_bf16 v[64:79], v[8:11], v[64:67], 0
	s_waitcnt vmcnt(0)
	ds_write_b128 v177, v[218:221]
	ds_write_b128 v178, v[222:225]
	ds_write_b128 v179, v[226:229]
	ds_write_b128 v180, v[238:241]
	ds_write_b128 v181, v[244:247]
	ds_write_b128 v182, v[248:251]
	v_mfma_f32_32x32x16_bf16 v[0:15], v[8:11], v[12:15], 0
	s_waitcnt lgkmcnt(0)
	s_barrier
	global_load_dwordx4 v[218:221], v[162:163], off offset:128
	global_load_dwordx4 v[222:225], v[164:165], off offset:128
	global_load_dwordx4 v[226:229], v[166:167], off offset:128
	global_load_dwordx4 v[238:241], v[170:171], off offset:128
	global_load_dwordx4 v[244:247], v[168:169], off offset:128
	global_load_dwordx4 v[248:251], v[172:173], off offset:128
	v_mfma_f32_32x32x16_bf16 v[96:111], v[194:197], v[190:193], v[96:111]
	v_mfma_f32_32x32x16_bf16 v[32:47], v[194:197], v[206:209], v[32:47]
	v_mfma_f32_32x32x16_bf16 v[80:95], v[198:201], v[190:193], v[80:95]
	v_mfma_f32_32x32x16_bf16 v[16:31], v[198:201], v[206:209], v[16:31]
	v_mfma_f32_32x32x16_bf16 v[64:79], v[202:205], v[190:193], v[64:79]
	v_mfma_f32_32x32x16_bf16 v[0:15], v[202:205], v[206:209], v[0:15]
	ds_read_b128 v[186:189], v175 offset:33280
	ds_read_b128 v[190:193], v175 offset:35840
	ds_read_b128 v[194:197], v175 offset:38400
	ds_read_b128 v[198:201], v176 offset:53760
	ds_read_b128 v[202:205], v175 offset:30720
	ds_read_b128 v[206:209], v175 offset:30752
	ds_read_b128 v[210:213], v176 offset:51200
	ds_read_b128 v[214:217], v176 offset:51232
	s_waitcnt lgkmcnt(1)
	v_mfma_f32_32x32x16_bf16 v[96:111], v[186:189], v[210:213], v[96:111]
	v_mfma_f32_32x32x16_bf16 v[32:47], v[186:189], v[198:201], v[32:47]
	v_mfma_f32_32x32x16_bf16 v[48:63], v[202:205], v[198:201], v[48:63]
	v_mfma_f32_32x32x16_bf16 v[80:95], v[190:193], v[210:213], v[80:95]
	v_mfma_f32_32x32x16_bf16 v[16:31], v[190:193], v[198:201], v[16:31]
	v_mfma_f32_32x32x16_bf16 v[64:79], v[194:197], v[210:213], v[64:79]
	v_mfma_f32_32x32x16_bf16 v[0:15], v[194:197], v[198:201], v[0:15]
	ds_read_b128 v[186:189], v175 offset:33312
	ds_read_b128 v[190:193], v175 offset:35872
	ds_read_b128 v[194:197], v175 offset:38432
	ds_read_b128 v[198:201], v176 offset:53792
	s_waitcnt lgkmcnt(3)
	v_mfma_f32_32x32x16_bf16 v[96:111], v[186:189], v[214:217], v[96:111]
	s_waitcnt lgkmcnt(0)
	v_mfma_f32_32x32x16_bf16 v[32:47], v[186:189], v[198:201], v[32:47]
	v_mfma_f32_32x32x16_bf16 v[112:127], v[202:205], v[210:213], v[112:127]
	v_mfma_f32_32x32x16_bf16 v[48:63], v[206:209], v[198:201], v[48:63]
	v_mfma_f32_32x32x16_bf16 v[80:95], v[190:193], v[214:217], v[80:95]
	v_mfma_f32_32x32x16_bf16 v[16:31], v[190:193], v[198:201], v[16:31]
	v_mfma_f32_32x32x16_bf16 v[64:79], v[194:197], v[214:217], v[64:79]
	s_waitcnt vmcnt(0)
	ds_write_b128 v149, v[218:221]
	ds_write_b128 v151, v[222:225]
	ds_write_b128 v153, v[226:229]
	ds_write_b128 v157, v[238:241]
	ds_write_b128 v159, v[244:247]
	ds_write_b128 v174, v[248:251]
	v_mfma_f32_32x32x16_bf16 v[0:15], v[194:197], v[198:201], v[0:15]
	s_waitcnt lgkmcnt(0)
	s_barrier
	global_load_dwordx4 v[218:221], v[162:163], off offset:192
	global_load_dwordx4 v[222:225], v[164:165], off offset:192
	global_load_dwordx4 v[226:229], v[166:167], off offset:192
	global_load_dwordx4 v[238:241], v[170:171], off offset:192
	global_load_dwordx4 v[244:247], v[168:169], off offset:192
	global_load_dwordx4 v[248:251], v[172:173], off offset:192
	v_mfma_f32_32x32x16_bf16 v[112:127], v[206:209], v[214:217], v[112:127]
	ds_read_b128 v[186:189], v175 offset:2560
	ds_read_b128 v[190:193], v175 offset:5120
	ds_read_b128 v[194:197], v175 offset:7680
	ds_read_b128 v[198:201], v176 offset:23040
	ds_read_b128 v[202:205], v175
	ds_read_b128 v[206:209], v175 offset:32
	ds_read_b128 v[210:213], v176 offset:20480
	ds_read_b128 v[214:217], v176 offset:20512
	s_waitcnt lgkmcnt(1)
	v_mfma_f32_32x32x16_bf16 v[96:111], v[186:189], v[210:213], v[96:111]
	v_mfma_f32_32x32x16_bf16 v[32:47], v[186:189], v[198:201], v[32:47]
	v_mfma_f32_32x32x16_bf16 v[48:63], v[202:205], v[198:201], v[48:63]
	v_mfma_f32_32x32x16_bf16 v[80:95], v[190:193], v[210:213], v[80:95]
	v_mfma_f32_32x32x16_bf16 v[16:31], v[190:193], v[198:201], v[16:31]
	v_mfma_f32_32x32x16_bf16 v[64:79], v[194:197], v[210:213], v[64:79]
	v_mfma_f32_32x32x16_bf16 v[0:15], v[194:197], v[198:201], v[0:15]
	ds_read_b128 v[186:189], v175 offset:2592
	ds_read_b128 v[190:193], v175 offset:5152
	ds_read_b128 v[194:197], v175 offset:7712
	ds_read_b128 v[198:201], v176 offset:23072
	s_waitcnt lgkmcnt(3)
	v_mfma_f32_32x32x16_bf16 v[96:111], v[186:189], v[214:217], v[96:111]
	s_waitcnt lgkmcnt(0)
	v_mfma_f32_32x32x16_bf16 v[32:47], v[186:189], v[198:201], v[32:47]
	v_mfma_f32_32x32x16_bf16 v[48:63], v[206:209], v[198:201], v[48:63]
	v_mfma_f32_32x32x16_bf16 v[80:95], v[190:193], v[214:217], v[80:95]
	v_mfma_f32_32x32x16_bf16 v[16:31], v[190:193], v[198:201], v[16:31]
	v_mfma_f32_32x32x16_bf16 v[64:79], v[194:197], v[214:217], v[64:79]
	v_mfma_f32_32x32x16_bf16 v[0:15], v[194:197], v[198:201], v[0:15]
	s_waitcnt vmcnt(0)
	ds_write_b128 v177, v[218:221]
	ds_write_b128 v178, v[222:225]
	ds_write_b128 v179, v[226:229]
	ds_write_b128 v180, v[238:241]
	ds_write_b128 v181, v[244:247]
	ds_write_b128 v182, v[248:251]
	v_mfma_f32_32x32x16_bf16 v[112:127], v[202:205], v[210:213], v[112:127]
	s_waitcnt lgkmcnt(0)
	s_barrier
	ds_read_b128 v[162:165], v175 offset:33280
	ds_read_b128 v[166:169], v175 offset:35840
	ds_read_b128 v[170:173], v175 offset:38400
	ds_read_b128 v[186:189], v176 offset:53760
	ds_read_b128 v[190:193], v175 offset:30720
	ds_read_b128 v[194:197], v175 offset:30752
	ds_read_b128 v[198:201], v176 offset:51200
	ds_read_b128 v[202:205], v176 offset:51232
	s_waitcnt lgkmcnt(1)
	v_mfma_f32_32x32x16_bf16 v[96:111], v[162:165], v[198:201], v[96:111]
	v_mfma_f32_32x32x16_bf16 v[32:47], v[162:165], v[186:189], v[32:47]
	v_mfma_f32_32x32x16_bf16 v[48:63], v[190:193], v[186:189], v[48:63]
	v_mfma_f32_32x32x16_bf16 v[80:95], v[166:169], v[198:201], v[80:95]
	v_mfma_f32_32x32x16_bf16 v[16:31], v[166:169], v[186:189], v[16:31]
	v_mfma_f32_32x32x16_bf16 v[64:79], v[170:173], v[198:201], v[64:79]
	v_mfma_f32_32x32x16_bf16 v[0:15], v[170:173], v[186:189], v[0:15]
	ds_read_b128 v[162:165], v175 offset:33312
	ds_read_b128 v[166:169], v175 offset:35872
	ds_read_b128 v[170:173], v175 offset:38432
	ds_read_b128 v[186:189], v176 offset:53792
	s_waitcnt lgkmcnt(0)
	s_barrier
	v_mfma_f32_32x32x16_bf16 v[96:111], v[162:165], v[202:205], v[96:111]
	v_mfma_f32_32x32x16_bf16 v[32:47], v[162:165], v[186:189], v[32:47]
	v_lshlrev_b32_e32 v162, 7, v184
	v_ashrrev_i32_e32 v163, 31, v162
	v_lshlrev_b64 v[132:133], 1, v[162:163]
	v_or_b32_e32 v164, v130, v156
	v_mov_b32_e32 v165, v131
	v_lshl_add_u64 v[134:135], s[94:95], 0, v[132:133]
	v_or_b32_e32 v136, v162, v156
	v_mfma_f32_32x32x16_bf16 v[80:95], v[166:169], v[202:205], v[80:95]
	v_ashrrev_i32_e32 v137, 31, v136
	v_lshl_add_u64 v[160:161], v[136:137], 2, s[76:77]
	global_load_dword v160, v[160:161], off
	v_lshl_add_u64 v[132:133], s[6:7], 0, v[132:133]
	v_or_b32_e32 v130, v130, v158
	v_mov_b32_e32 v137, v163
	s_waitcnt vmcnt(0)
	v_pk_add_f32 v[96:97], v[96:97], v[160:161] op_sel_hi:[1,0]
	v_mfma_f32_32x32x16_bf16 v[16:31], v[166:169], v[186:189], v[16:31]
	v_lshlrev_b64 v[166:167], 12, v[164:165]
	v_lshl_add_u64 v[166:167], v[134:135], 0, v[166:167]
	v_lshl_add_u64 v[166:167], v[166:167], 0, v[128:129]
	global_load_dwordx2 v[168:169], v[166:167], off
	v_lshlrev_b64 v[164:165], 11, v[164:165]
	v_lshl_add_u64 v[164:165], v[132:133], 0, v[164:165]
	v_pk_add_f32 v[98:99], v[98:99], v[160:161] op_sel_hi:[1,0]
	v_mfma_f32_32x32x16_bf16 v[112:127], v[206:209], v[214:217], v[112:127]
	v_add_f32_e64 v100, v100, v160
	v_add_f32_e64 v101, v101, v160
	v_add_f32_e64 v80, v80, v160
	v_add_f32_e64 v81, v81, v160
	v_add_f32_e64 v82, v82, v160
	v_add_f32_e64 v83, v83, v160
	v_pk_add_f32 v[84:85], v[84:85], v[160:161] op_sel_hi:[1,0]
	v_mfma_f32_32x32x16_bf16 v[112:127], v[190:193], v[198:201], v[112:127]
	v_mfma_f32_32x32x16_bf16 v[112:127], v[194:197], v[202:205], v[112:127]
	v_mfma_f32_32x32x16_bf16 v[64:79], v[170:173], v[202:205], v[64:79]
	s_nop 10
	v_add_f32_e64 v112, v112, v160
	v_add_f32_e64 v113, v113, v160
	v_add_f32_e64 v114, v114, v160
	v_add_f32_e64 v115, v115, v160
	v_add_f32_e64 v116, v116, v160
	v_add_f32_e64 v117, v117, v160
	v_pk_add_f32 v[118:119], v[118:119], v[160:161] op_sel_hi:[1,0]
	v_mfma_f32_32x32x16_bf16 v[0:15], v[170:173], v[186:189], v[0:15]
	v_add_f32_e64 v64, v64, v160
	v_add_f32_e64 v65, v65, v160
	v_add_f32_e64 v66, v66, v160
	v_add_f32_e64 v67, v67, v160
	v_add_f32_e64 v68, v68, v160
	v_add_f32_e64 v69, v69, v160
	s_waitcnt vmcnt(0)
	v_lshlrev_b32_e32 v170, 16, v168
	v_and_b32_e32 v171, 0xffff0000, v168
	v_lshlrev_b32_e32 v168, 16, v169
	v_and_b32_e32 v169, 0xffff0000, v169
	v_pk_mul_f32 v[112:113], v[112:113], v[170:171]
	v_pk_mul_f32 v[114:115], v[114:115], v[168:169]
	v_cvt_pk_bf16_f32 v112, v112, v113
	v_cvt_pk_bf16_f32 v113, v114, v115
	v_lshl_add_u64 v[114:115], v[164:165], 0, v[128:129]
	global_store_dwordx2 v[114:115], v[112:113], off
	global_load_dwordx2 v[112:113], v[166:167], off offset:16
	v_mfma_f32_32x32x16_bf16 v[48:63], v[194:197], v[186:189], v[48:63]
	s_waitcnt vmcnt(0)
	v_lshlrev_b32_e32 v164, 16, v112
	v_and_b32_e32 v165, 0xffff0000, v112
	v_lshlrev_b32_e32 v112, 16, v113
	v_and_b32_e32 v113, 0xffff0000, v113
	v_pk_mul_f32 v[116:117], v[116:117], v[164:165]
	v_pk_mul_f32 v[112:113], v[118:119], v[112:113]
	v_cvt_pk_bf16_f32 v116, v116, v117
	v_cvt_pk_bf16_f32 v117, v112, v113
	global_load_dwordx2 v[112:113], v[166:167], off offset:32
	v_pk_add_f32 v[118:119], v[120:121], v[160:161] op_sel_hi:[1,0]
	global_store_dwordx2 v[114:115], v[116:117], off offset:16
	s_waitcnt vmcnt(1)
	v_lshlrev_b32_e32 v116, 16, v112
	v_and_b32_e32 v117, 0xffff0000, v112
	v_pk_mul_f32 v[116:117], v[118:119], v[116:117]
	v_lshlrev_b32_e32 v112, 16, v113
	v_and_b32_e32 v113, 0xffff0000, v113
	v_pk_add_f32 v[118:119], v[122:123], v[160:161] op_sel_hi:[1,0]
	v_cvt_pk_bf16_f32 v116, v116, v117
	v_pk_mul_f32 v[112:113], v[118:119], v[112:113]
	v_pk_add_f32 v[118:119], v[124:125], v[160:161] op_sel_hi:[1,0]
	v_cvt_pk_bf16_f32 v117, v112, v113
	global_load_dwordx2 v[112:113], v[166:167], off offset:48
	s_nop 0
	global_store_dwordx2 v[114:115], v[116:117], off offset:32
	s_waitcnt vmcnt(1)
	v_lshlrev_b32_e32 v116, 16, v112
	v_and_b32_e32 v117, 0xffff0000, v112
	v_pk_mul_f32 v[116:117], v[118:119], v[116:117]
	v_lshlrev_b32_e32 v112, 16, v113
	v_and_b32_e32 v113, 0xffff0000, v113
	v_pk_add_f32 v[118:119], v[126:127], v[160:161] op_sel_hi:[1,0]
	v_cvt_pk_bf16_f32 v116, v116, v117
	v_pk_mul_f32 v[112:113], v[118:119], v[112:113]
	s_nop 0
	v_cvt_pk_bf16_f32 v117, v112, v113
	global_load_dwordx2 v[112:113], v[166:167], off offset:64
	s_nop 0
	global_store_dwordx2 v[114:115], v[116:117], off offset:48
	s_waitcnt vmcnt(1)
	v_lshlrev_b32_e32 v116, 16, v112
	v_and_b32_e32 v117, 0xffff0000, v112
	v_lshlrev_b32_e32 v112, 16, v113
	v_and_b32_e32 v113, 0xffff0000, v113
	v_pk_mul_f32 v[96:97], v[96:97], v[116:117]
	v_pk_mul_f32 v[98:99], v[98:99], v[112:113]
	v_cvt_pk_bf16_f32 v96, v96, v97
	v_cvt_pk_bf16_f32 v97, v98, v99
	global_store_dwordx2 v[114:115], v[96:97], off offset:64
	global_load_dwordx2 v[96:97], v[166:167], off offset:80
	s_waitcnt vmcnt(0)
	v_lshlrev_b32_e32 v98, 16, v96
	v_and_b32_e32 v99, 0xffff0000, v96
	v_pk_mul_f32 v[98:99], v[100:101], v[98:99]
	v_lshlrev_b32_e32 v96, 16, v97
	v_and_b32_e32 v97, 0xffff0000, v97
	v_pk_add_f32 v[100:101], v[102:103], v[160:161] op_sel_hi:[1,0]
	v_cvt_pk_bf16_f32 v98, v98, v99
	v_pk_mul_f32 v[96:97], v[100:101], v[96:97]
	v_pk_add_f32 v[100:101], v[104:105], v[160:161] op_sel_hi:[1,0]
	v_cvt_pk_bf16_f32 v99, v96, v97
	global_load_dwordx2 v[96:97], v[166:167], off offset:96
	s_nop 0
	global_store_dwordx2 v[114:115], v[98:99], off offset:80
	s_waitcnt vmcnt(1)
	v_lshlrev_b32_e32 v98, 16, v96
	v_and_b32_e32 v99, 0xffff0000, v96
	v_pk_mul_f32 v[98:99], v[100:101], v[98:99]
	v_lshlrev_b32_e32 v96, 16, v97
	v_and_b32_e32 v97, 0xffff0000, v97
	v_pk_add_f32 v[100:101], v[106:107], v[160:161] op_sel_hi:[1,0]
	v_cvt_pk_bf16_f32 v98, v98, v99
	v_pk_mul_f32 v[96:97], v[100:101], v[96:97]
	v_pk_add_f32 v[100:101], v[108:109], v[160:161] op_sel_hi:[1,0]
	v_cvt_pk_bf16_f32 v99, v96, v97
	global_load_dwordx2 v[96:97], v[166:167], off offset:112
	s_nop 0
	global_store_dwordx2 v[114:115], v[98:99], off offset:96
	s_waitcnt vmcnt(1)
	v_lshlrev_b32_e32 v98, 16, v96
	v_and_b32_e32 v99, 0xffff0000, v96
	v_pk_mul_f32 v[98:99], v[100:101], v[98:99]
	v_lshlrev_b32_e32 v96, 16, v97
	v_and_b32_e32 v97, 0xffff0000, v97
	v_pk_add_f32 v[100:101], v[110:111], v[160:161] op_sel_hi:[1,0]
	v_cvt_pk_bf16_f32 v98, v98, v99
	v_pk_mul_f32 v[96:97], v[100:101], v[96:97]
	s_nop 0
	v_cvt_pk_bf16_f32 v99, v96, v97
	global_load_dwordx2 v[96:97], v[166:167], off offset:128
	s_nop 0
	global_store_dwordx2 v[114:115], v[98:99], off offset:112
	s_waitcnt vmcnt(1)
	v_lshlrev_b32_e32 v98, 16, v96
	v_and_b32_e32 v99, 0xffff0000, v96
	v_lshlrev_b32_e32 v96, 16, v97
	v_and_b32_e32 v97, 0xffff0000, v97
	v_pk_mul_f32 v[80:81], v[80:81], v[98:99]
	v_pk_mul_f32 v[82:83], v[82:83], v[96:97]
	v_cvt_pk_bf16_f32 v80, v80, v81
	v_cvt_pk_bf16_f32 v81, v82, v83
	global_store_dwordx2 v[114:115], v[80:81], off offset:128
	global_load_dwordx2 v[80:81], v[166:167], off offset:144
	s_waitcnt vmcnt(0)
	v_lshlrev_b32_e32 v82, 16, v80
	v_and_b32_e32 v83, 0xffff0000, v80
	v_pk_mul_f32 v[82:83], v[84:85], v[82:83]
	v_lshlrev_b32_e32 v80, 16, v81
	v_and_b32_e32 v81, 0xffff0000, v81
	v_pk_add_f32 v[84:85], v[86:87], v[160:161] op_sel_hi:[1,0]
	v_cvt_pk_bf16_f32 v82, v82, v83
	v_pk_mul_f32 v[80:81], v[84:85], v[80:81]
	v_pk_add_f32 v[84:85], v[88:89], v[160:161] op_sel_hi:[1,0]
	v_cvt_pk_bf16_f32 v83, v80, v81
	global_load_dwordx2 v[80:81], v[166:167], off offset:160
	s_nop 0
	global_store_dwordx2 v[114:115], v[82:83], off offset:144
	s_waitcnt vmcnt(1)
	v_lshlrev_b32_e32 v82, 16, v80
	v_and_b32_e32 v83, 0xffff0000, v80
	v_pk_mul_f32 v[82:83], v[84:85], v[82:83]
	v_lshlrev_b32_e32 v80, 16, v81
	v_and_b32_e32 v81, 0xffff0000, v81
	v_pk_add_f32 v[84:85], v[90:91], v[160:161] op_sel_hi:[1,0]
	v_cvt_pk_bf16_f32 v82, v82, v83
	v_pk_mul_f32 v[80:81], v[84:85], v[80:81]
	v_pk_add_f32 v[84:85], v[92:93], v[160:161] op_sel_hi:[1,0]
	v_cvt_pk_bf16_f32 v83, v80, v81
	global_load_dwordx2 v[80:81], v[166:167], off offset:176
	s_nop 0
	global_store_dwordx2 v[114:115], v[82:83], off offset:160
	s_waitcnt vmcnt(1)
	v_lshlrev_b32_e32 v82, 16, v80
	v_and_b32_e32 v83, 0xffff0000, v80
	v_pk_mul_f32 v[82:83], v[84:85], v[82:83]
	v_lshlrev_b32_e32 v80, 16, v81
	v_and_b32_e32 v81, 0xffff0000, v81
	v_pk_add_f32 v[84:85], v[94:95], v[160:161] op_sel_hi:[1,0]
	v_cvt_pk_bf16_f32 v82, v82, v83
	v_pk_mul_f32 v[80:81], v[84:85], v[80:81]
	s_nop 0
	v_cvt_pk_bf16_f32 v83, v80, v81
	global_load_dwordx2 v[80:81], v[166:167], off offset:192
	s_nop 0
	global_store_dwordx2 v[114:115], v[82:83], off offset:176
	s_waitcnt vmcnt(1)
	v_lshlrev_b32_e32 v82, 16, v80
	v_and_b32_e32 v83, 0xffff0000, v80
	v_lshlrev_b32_e32 v80, 16, v81
	v_and_b32_e32 v81, 0xffff0000, v81
	v_pk_mul_f32 v[64:65], v[64:65], v[82:83]
	v_pk_mul_f32 v[66:67], v[66:67], v[80:81]
	v_cvt_pk_bf16_f32 v64, v64, v65
	v_cvt_pk_bf16_f32 v65, v66, v67
	global_store_dwordx2 v[114:115], v[64:65], off offset:192
	global_load_dwordx2 v[64:65], v[166:167], off offset:208
	s_waitcnt vmcnt(0)
	v_lshlrev_b32_e32 v66, 16, v64
	v_and_b32_e32 v67, 0xffff0000, v64
	v_pk_mul_f32 v[66:67], v[68:69], v[66:67]
	v_lshlrev_b32_e32 v64, 16, v65
	v_and_b32_e32 v65, 0xffff0000, v65
	v_pk_add_f32 v[68:69], v[70:71], v[160:161] op_sel_hi:[1,0]
	v_cvt_pk_bf16_f32 v66, v66, v67
	v_pk_mul_f32 v[64:65], v[68:69], v[64:65]
	v_pk_add_f32 v[68:69], v[72:73], v[160:161] op_sel_hi:[1,0]
	v_cvt_pk_bf16_f32 v67, v64, v65
	global_load_dwordx2 v[64:65], v[166:167], off offset:224
	s_nop 0
	global_store_dwordx2 v[114:115], v[66:67], off offset:208
	s_waitcnt vmcnt(1)
	v_lshlrev_b32_e32 v66, 16, v64
	v_and_b32_e32 v67, 0xffff0000, v64
	v_pk_mul_f32 v[66:67], v[68:69], v[66:67]
	v_lshlrev_b32_e32 v64, 16, v65
	v_and_b32_e32 v65, 0xffff0000, v65
	v_pk_add_f32 v[68:69], v[74:75], v[160:161] op_sel_hi:[1,0]
	v_cvt_pk_bf16_f32 v66, v66, v67
	v_pk_mul_f32 v[64:65], v[68:69], v[64:65]
	v_pk_add_f32 v[68:69], v[76:77], v[160:161] op_sel_hi:[1,0]
	v_cvt_pk_bf16_f32 v67, v64, v65
	global_load_dwordx2 v[64:65], v[166:167], off offset:240
	s_nop 0
	global_store_dwordx2 v[114:115], v[66:67], off offset:224
	s_waitcnt vmcnt(1)
	v_lshlrev_b32_e32 v66, 16, v64
	v_and_b32_e32 v67, 0xffff0000, v64
	v_pk_mul_f32 v[66:67], v[68:69], v[66:67]
	v_lshlrev_b32_e32 v64, 16, v65
	v_and_b32_e32 v65, 0xffff0000, v65
	v_pk_add_f32 v[68:69], v[78:79], v[160:161] op_sel_hi:[1,0]
	v_cvt_pk_bf16_f32 v66, v66, v67
	v_pk_mul_f32 v[64:65], v[68:69], v[64:65]
	v_lshlrev_b64 v[68:69], 11, v[130:131]
	v_cvt_pk_bf16_f32 v67, v64, v65
	global_store_dwordx2 v[114:115], v[66:67], off offset:240
	v_lshlrev_b64 v[66:67], 12, v[130:131]
	v_lshl_add_u64 v[66:67], v[134:135], 0, v[66:67]
	v_lshl_add_u64 v[64:65], v[136:137], 2, s[76:77]
	v_lshl_add_u64 v[66:67], v[66:67], 0, v[128:129]
	global_load_dword v64, v[64:65], off offset:128
	v_lshl_add_u64 v[68:69], v[132:133], 0, v[68:69]
	global_load_dwordx2 v[70:71], v[66:67], off
	s_waitcnt vmcnt(1)
	v_pk_add_f32 v[48:49], v[48:49], v[64:65] op_sel_hi:[1,0]
	v_pk_add_f32 v[50:51], v[50:51], v[64:65] op_sel_hi:[1,0]
	s_waitcnt vmcnt(0)
	v_lshlrev_b32_e32 v72, 16, v70
	v_and_b32_e32 v73, 0xffff0000, v70
	v_lshlrev_b32_e32 v70, 16, v71
	v_and_b32_e32 v71, 0xffff0000, v71
	v_pk_mul_f32 v[48:49], v[48:49], v[72:73]
	v_pk_mul_f32 v[50:51], v[50:51], v[70:71]
	v_cvt_pk_bf16_f32 v48, v48, v49
	v_cvt_pk_bf16_f32 v49, v50, v51
	v_lshl_add_u64 v[50:51], v[68:69], 0, v[128:129]
	global_store_dwordx2 v[50:51], v[48:49], off
	global_load_dwordx2 v[48:49], v[66:67], off offset:16
	v_pk_add_f32 v[52:53], v[52:53], v[64:65] op_sel_hi:[1,0]
	v_pk_add_f32 v[54:55], v[54:55], v[64:65] op_sel_hi:[1,0]
	v_pk_add_f32 v[32:33], v[32:33], v[64:65] op_sel_hi:[1,0]
	v_pk_add_f32 v[34:35], v[34:35], v[64:65] op_sel_hi:[1,0]
	v_pk_add_f32 v[36:37], v[36:37], v[64:65] op_sel_hi:[1,0]
	v_pk_add_f32 v[16:17], v[16:17], v[64:65] op_sel_hi:[1,0]
	v_pk_add_f32 v[18:19], v[18:19], v[64:65] op_sel_hi:[1,0]
	v_pk_add_f32 v[20:21], v[20:21], v[64:65] op_sel_hi:[1,0]
	v_pk_add_f32 v[0:1], v[0:1], v[64:65] op_sel_hi:[1,0]
	v_pk_add_f32 v[2:3], v[2:3], v[64:65] op_sel_hi:[1,0]
	v_pk_add_f32 v[4:5], v[4:5], v[64:65] op_sel_hi:[1,0]
	s_waitcnt vmcnt(0)
	v_lshlrev_b32_e32 v68, 16, v48
	v_and_b32_e32 v69, 0xffff0000, v48
	v_lshlrev_b32_e32 v48, 16, v49
	v_and_b32_e32 v49, 0xffff0000, v49
	v_pk_mul_f32 v[52:53], v[52:53], v[68:69]
	v_pk_mul_f32 v[48:49], v[54:55], v[48:49]
	v_cvt_pk_bf16_f32 v52, v52, v53
	v_cvt_pk_bf16_f32 v53, v48, v49
	global_load_dwordx2 v[48:49], v[66:67], off offset:32
	v_pk_add_f32 v[54:55], v[56:57], v[64:65] op_sel_hi:[1,0]
	global_store_dwordx2 v[50:51], v[52:53], off offset:16
	s_waitcnt vmcnt(1)
	v_lshlrev_b32_e32 v52, 16, v48
	v_and_b32_e32 v53, 0xffff0000, v48
	v_pk_mul_f32 v[52:53], v[54:55], v[52:53]
	v_lshlrev_b32_e32 v48, 16, v49
	v_and_b32_e32 v49, 0xffff0000, v49
	v_pk_add_f32 v[54:55], v[58:59], v[64:65] op_sel_hi:[1,0]
	v_cvt_pk_bf16_f32 v52, v52, v53
	v_pk_mul_f32 v[48:49], v[54:55], v[48:49]
	v_pk_add_f32 v[54:55], v[60:61], v[64:65] op_sel_hi:[1,0]
	v_cvt_pk_bf16_f32 v53, v48, v49
	global_load_dwordx2 v[48:49], v[66:67], off offset:48
	s_nop 0
	global_store_dwordx2 v[50:51], v[52:53], off offset:32
	s_waitcnt vmcnt(1)
	v_lshlrev_b32_e32 v52, 16, v48
	v_and_b32_e32 v53, 0xffff0000, v48
	v_pk_mul_f32 v[52:53], v[54:55], v[52:53]
	v_lshlrev_b32_e32 v48, 16, v49
	v_and_b32_e32 v49, 0xffff0000, v49
	v_pk_add_f32 v[54:55], v[62:63], v[64:65] op_sel_hi:[1,0]
	v_cvt_pk_bf16_f32 v52, v52, v53
	v_pk_mul_f32 v[48:49], v[54:55], v[48:49]
	s_nop 0
	v_cvt_pk_bf16_f32 v53, v48, v49
	global_load_dwordx2 v[48:49], v[66:67], off offset:64
	s_nop 0
	global_store_dwordx2 v[50:51], v[52:53], off offset:48
	s_waitcnt vmcnt(1)
	v_lshlrev_b32_e32 v52, 16, v48
	v_and_b32_e32 v53, 0xffff0000, v48
	v_lshlrev_b32_e32 v48, 16, v49
	v_and_b32_e32 v49, 0xffff0000, v49
	v_pk_mul_f32 v[32:33], v[32:33], v[52:53]
	v_pk_mul_f32 v[34:35], v[34:35], v[48:49]
	v_cvt_pk_bf16_f32 v32, v32, v33
	v_cvt_pk_bf16_f32 v33, v34, v35
	global_store_dwordx2 v[50:51], v[32:33], off offset:64
	global_load_dwordx2 v[32:33], v[66:67], off offset:80
	s_waitcnt vmcnt(0)
	v_lshlrev_b32_e32 v34, 16, v32
	v_and_b32_e32 v35, 0xffff0000, v32
	v_pk_mul_f32 v[34:35], v[36:37], v[34:35]
	v_lshlrev_b32_e32 v32, 16, v33
	v_and_b32_e32 v33, 0xffff0000, v33
	v_pk_add_f32 v[36:37], v[38:39], v[64:65] op_sel_hi:[1,0]
	v_cvt_pk_bf16_f32 v34, v34, v35
	v_pk_mul_f32 v[32:33], v[36:37], v[32:33]
	v_pk_add_f32 v[36:37], v[40:41], v[64:65] op_sel_hi:[1,0]
	v_cvt_pk_bf16_f32 v35, v32, v33
	global_load_dwordx2 v[32:33], v[66:67], off offset:96
	s_nop 0
	global_store_dwordx2 v[50:51], v[34:35], off offset:80
	s_waitcnt vmcnt(1)
	v_lshlrev_b32_e32 v34, 16, v32
	v_and_b32_e32 v35, 0xffff0000, v32
	v_pk_mul_f32 v[34:35], v[36:37], v[34:35]
	v_lshlrev_b32_e32 v32, 16, v33
	v_and_b32_e32 v33, 0xffff0000, v33
	v_pk_add_f32 v[36:37], v[42:43], v[64:65] op_sel_hi:[1,0]
	v_cvt_pk_bf16_f32 v34, v34, v35
	v_pk_mul_f32 v[32:33], v[36:37], v[32:33]
	v_pk_add_f32 v[36:37], v[44:45], v[64:65] op_sel_hi:[1,0]
	v_cvt_pk_bf16_f32 v35, v32, v33
	global_load_dwordx2 v[32:33], v[66:67], off offset:112
	s_nop 0
	global_store_dwordx2 v[50:51], v[34:35], off offset:96
	s_waitcnt vmcnt(1)
	v_lshlrev_b32_e32 v34, 16, v32
	v_and_b32_e32 v35, 0xffff0000, v32
	v_pk_mul_f32 v[34:35], v[36:37], v[34:35]
	v_lshlrev_b32_e32 v32, 16, v33
	v_and_b32_e32 v33, 0xffff0000, v33
	v_pk_add_f32 v[36:37], v[46:47], v[64:65] op_sel_hi:[1,0]
	v_cvt_pk_bf16_f32 v34, v34, v35
	v_pk_mul_f32 v[32:33], v[36:37], v[32:33]
	s_nop 0
	v_cvt_pk_bf16_f32 v35, v32, v33
	global_load_dwordx2 v[32:33], v[66:67], off offset:128
	s_nop 0
	global_store_dwordx2 v[50:51], v[34:35], off offset:112
	s_waitcnt vmcnt(1)
	v_lshlrev_b32_e32 v34, 16, v32
	v_and_b32_e32 v35, 0xffff0000, v32
	v_lshlrev_b32_e32 v32, 16, v33
	v_and_b32_e32 v33, 0xffff0000, v33
	v_pk_mul_f32 v[16:17], v[16:17], v[34:35]
	v_pk_mul_f32 v[18:19], v[18:19], v[32:33]
	v_cvt_pk_bf16_f32 v16, v16, v17
	v_cvt_pk_bf16_f32 v17, v18, v19
	global_store_dwordx2 v[50:51], v[16:17], off offset:128
	global_load_dwordx2 v[16:17], v[66:67], off offset:144
	s_waitcnt vmcnt(0)
	v_lshlrev_b32_e32 v18, 16, v16
	v_and_b32_e32 v19, 0xffff0000, v16
	v_pk_mul_f32 v[18:19], v[20:21], v[18:19]
	v_lshlrev_b32_e32 v16, 16, v17
	v_and_b32_e32 v17, 0xffff0000, v17
	v_pk_add_f32 v[20:21], v[22:23], v[64:65] op_sel_hi:[1,0]
	v_cvt_pk_bf16_f32 v18, v18, v19
	v_pk_mul_f32 v[16:17], v[20:21], v[16:17]
	v_pk_add_f32 v[20:21], v[24:25], v[64:65] op_sel_hi:[1,0]
	v_cvt_pk_bf16_f32 v19, v16, v17
	global_load_dwordx2 v[16:17], v[66:67], off offset:160
	s_nop 0
	global_store_dwordx2 v[50:51], v[18:19], off offset:144
	s_waitcnt vmcnt(1)
	v_lshlrev_b32_e32 v18, 16, v16
	v_and_b32_e32 v19, 0xffff0000, v16
	v_pk_mul_f32 v[18:19], v[20:21], v[18:19]
	v_lshlrev_b32_e32 v16, 16, v17
	v_and_b32_e32 v17, 0xffff0000, v17
	v_pk_add_f32 v[20:21], v[26:27], v[64:65] op_sel_hi:[1,0]
	v_cvt_pk_bf16_f32 v18, v18, v19
	v_pk_mul_f32 v[16:17], v[20:21], v[16:17]
	v_pk_add_f32 v[20:21], v[28:29], v[64:65] op_sel_hi:[1,0]
	v_cvt_pk_bf16_f32 v19, v16, v17
	global_load_dwordx2 v[16:17], v[66:67], off offset:176
	s_nop 0
	global_store_dwordx2 v[50:51], v[18:19], off offset:160
	s_waitcnt vmcnt(1)
	v_lshlrev_b32_e32 v18, 16, v16
	v_and_b32_e32 v19, 0xffff0000, v16
	v_pk_mul_f32 v[18:19], v[20:21], v[18:19]
	v_lshlrev_b32_e32 v16, 16, v17
	v_and_b32_e32 v17, 0xffff0000, v17
	v_pk_add_f32 v[20:21], v[30:31], v[64:65] op_sel_hi:[1,0]
	v_cvt_pk_bf16_f32 v18, v18, v19
	v_pk_mul_f32 v[16:17], v[20:21], v[16:17]
	s_nop 0
	v_cvt_pk_bf16_f32 v19, v16, v17
	global_load_dwordx2 v[16:17], v[66:67], off offset:192
	s_nop 0
	global_store_dwordx2 v[50:51], v[18:19], off offset:176
	s_waitcnt vmcnt(1)
	v_lshlrev_b32_e32 v18, 16, v16
	v_and_b32_e32 v19, 0xffff0000, v16
	v_lshlrev_b32_e32 v16, 16, v17
	v_and_b32_e32 v17, 0xffff0000, v17
	v_pk_mul_f32 v[0:1], v[0:1], v[18:19]
	v_pk_mul_f32 v[2:3], v[2:3], v[16:17]
	v_cvt_pk_bf16_f32 v0, v0, v1
	v_cvt_pk_bf16_f32 v1, v2, v3
	global_store_dwordx2 v[50:51], v[0:1], off offset:192
	global_load_dwordx2 v[0:1], v[66:67], off offset:208
	s_waitcnt vmcnt(0)
	v_lshlrev_b32_e32 v2, 16, v0
	v_and_b32_e32 v3, 0xffff0000, v0
	v_pk_mul_f32 v[2:3], v[4:5], v[2:3]
	v_lshlrev_b32_e32 v0, 16, v1
	v_and_b32_e32 v1, 0xffff0000, v1
	v_pk_add_f32 v[4:5], v[6:7], v[64:65] op_sel_hi:[1,0]
	v_cvt_pk_bf16_f32 v2, v2, v3
	v_pk_mul_f32 v[0:1], v[4:5], v[0:1]
	v_pk_add_f32 v[4:5], v[8:9], v[64:65] op_sel_hi:[1,0]
	v_cvt_pk_bf16_f32 v3, v0, v1
	global_load_dwordx2 v[0:1], v[66:67], off offset:224
	s_nop 0
	global_store_dwordx2 v[50:51], v[2:3], off offset:208
	s_waitcnt vmcnt(1)
	v_lshlrev_b32_e32 v2, 16, v0
	v_and_b32_e32 v3, 0xffff0000, v0
	v_pk_mul_f32 v[2:3], v[4:5], v[2:3]
	v_lshlrev_b32_e32 v0, 16, v1
	v_and_b32_e32 v1, 0xffff0000, v1
	v_pk_add_f32 v[4:5], v[10:11], v[64:65] op_sel_hi:[1,0]
	v_cvt_pk_bf16_f32 v2, v2, v3
	v_pk_mul_f32 v[0:1], v[4:5], v[0:1]
	v_pk_add_f32 v[4:5], v[12:13], v[64:65] op_sel_hi:[1,0]
	v_cvt_pk_bf16_f32 v3, v0, v1
	global_load_dwordx2 v[0:1], v[66:67], off offset:240
	s_nop 0
	global_store_dwordx2 v[50:51], v[2:3], off offset:224
	s_waitcnt vmcnt(1)
	v_lshlrev_b32_e32 v2, 16, v0
	v_and_b32_e32 v3, 0xffff0000, v0
	v_pk_mul_f32 v[2:3], v[4:5], v[2:3]
	v_lshlrev_b32_e32 v0, 16, v1
	v_and_b32_e32 v1, 0xffff0000, v1
	v_pk_add_f32 v[4:5], v[14:15], v[64:65] op_sel_hi:[1,0]
	v_cvt_pk_bf16_f32 v2, v2, v3
	v_pk_mul_f32 v[0:1], v[4:5], v[0:1]
	s_nop 0
	v_cvt_pk_bf16_f32 v3, v0, v1
	global_store_dwordx2 v[50:51], v[2:3], off offset:240
	s_andn2_b64 exec, exec, s[8:9]
	s_cbranch_execnz .LBB0_169
